# FFN-down tail rebalanced: GEMM-unit owners take the 256 latent hyena filter items after their unit, idle workgroups keep context filters + weight copies
# baseline (speedup 1.0000x reference)
.LBB0_346:
	s_mul_hi_u32 s6, s77, 0x280
	s_mul_i32 s6, s6, s76
	s_sub_i32 s6, 0x280, s6
	s_sub_i32 s7, s6, s76
	s_cmp_ge_u32 s6, s76
	s_cselect_b32 s6, s7, s6
	s_sub_i32 s7, s6, s76
	s_cmp_ge_u32 s6, s76
	s_cselect_b32 s74, s7, s6
	s_sub_i32 s10, s42, s74
	s_cmp_lt_i32 s2, s74
	s_cselect_b64 s[6:7], -1, 0
	s_and_b64 s[8:9], s[6:7], exec
	s_cselect_b32 s10, 0, s10
	s_cmp_eq_u32 s74, 0
	s_waitcnt lgkmcnt(0)
	s_cselect_b64 s[24:25], -1, 0
	s_and_b64 s[8:9], s[24:25], exec
	s_cselect_b32 s44, s42, s10
	s_sub_i32 s100, s2, s74
	s_cmp_lt_i32 s2, s74
	s_cselect_b32 s100, 0, s100
	s_cmp_eq_u32 s74, 0
	s_cselect_b32 s100, s2, s100
	s_mov_b32 s101, s44
	s_cmpk_lg_i32 s42, 0x100
	s_cbranch_scc1 .Lfilt_generic
	s_movk_i32 s101, 0x80
	s_add_i32 s100, s2, 0x80
	s_cmpk_lt_i32 s2, 0x80
	s_cselect_b32 s100, s2, s100
	s_branch .Lfilt_go
.Lfilt_generic:
	s_cmp_eq_u32 s44, 0
	s_cbranch_scc1 .LBB0_408
.Lfilt_go:
	s_sub_i32 s8, s2, s74
	s_and_b64 s[6:7], s[6:7], exec
	s_cselect_b32 s8, 0, s8
	s_and_b64 s[6:7], s[24:25], exec
	s_cselect_b32 s47, s2, s8
	s_cmpk_gt_i32 s100, 0x10f
	s_cbranch_scc1 .Lfilt_copies
	v_lshl_add_u64 v[10:11], s[12:13], 0, v[200:201]
	s_mov_b64 s[8:9], 0x100
	v_mov_b32_e32 v3, 0
	v_mov_b32_e32 v2, v200
	v_lshl_add_u64 v[10:11], v[10:11], 0, s[8:9]
	v_lshrrev_b32_e32 v37, 6, v218
	s_movk_i32 s8, 0x84
	s_movk_i32 s6, 0x210
	v_lshl_add_u64 v[4:5], s[14:15], 0, v[2:3]
	v_lshl_add_u64 v[6:7], s[30:31], 0, v[2:3]
	v_lshl_add_u64 v[8:9], s[18:19], 0, v[2:3]
	v_lshlrev_b32_e32 v2, 2, v218
	v_mad_u32_u24 v38, v37, s8, 16
	v_lshl_add_u64 v[12:13], s[16:17], 0, v[200:201]
	s_mov_b64 s[8:9], 0x200
	v_cmp_gt_u32_e64 s[6:7], s6, v218
	v_add_u32_e32 v36, 16, v2
	v_lshl_add_u64 v[12:13], v[12:13], 0, s[8:9]
	v_lshl_add_u64 v[14:15], s[28:29], 0, v[2:3]
	s_mov_b32 s15, 0
	v_mov_b32_e32 v39, 0x38d1b717
	s_brev_b32 s50, 18
	s_mov_b32 s51, 0xfe5163ab
	s_mov_b32 s56, 0x3c439041
	s_mov_b32 s57, 0xdb629599
	s_mov_b32 s58, 0xf534ddc0
	s_mov_b32 s59, 0xfc2757d1
	s_mov_b32 s60, 0x4e441529
	s_mov_b32 s61, 0xa2f9836e
	s_mov_b32 s62, 0x3fc90fda
	s_mov_b32 s63, 0x3f22f983
	s_mov_b32 s64, 0xbfc90fda
	v_mov_b32_e32 v40, 0x3c0881c4
	v_mov_b32_e32 v41, 0xbab64f3b
	s_movk_i32 s65, 0x1f8
	s_movk_i32 s66, 0x1ff
	s_add_i32 s67, 16, 0x840
	v_mov_b32_e32 v42, 0x40447cbd
	v_not_b32_e32 v43, 63
	v_not_b32_e32 v44, 31
	v_mov_b32_e32 v45, 0xffc00000
	v_mov_b32_e32 v46, 0x7fc00000
	s_mov_b32 s68, s100
	s_branch .LBB0_350
.LBB0_349:
	s_add_i32 s68, s68, s101
	s_cmpk_gt_i32 s68, 0x10f
	s_cbranch_scc1 .Lfilt_copies

	.amdhsa_kernel _Z8mega_fwd6Params
		.amdhsa_group_segment_fixed_size 16
		.amdhsa_private_segment_fixed_size 0
		.amdhsa_kernarg_size 536
		.amdhsa_user_sgpr_count 2
		.amdhsa_user_sgpr_dispatch_ptr 0
		.amdhsa_user_sgpr_queue_ptr 0
		.amdhsa_user_sgpr_kernarg_segment_ptr 1
		.amdhsa_user_sgpr_dispatch_id 0
		.amdhsa_user_sgpr_kernarg_preload_length 0
		.amdhsa_user_sgpr_kernarg_preload_offset 0
		.amdhsa_user_sgpr_private_segment_size 0
		.amdhsa_uses_dynamic_stack 0
		.amdhsa_enable_private_segment 0
		.amdhsa_system_sgpr_workgroup_id_x 1
		.amdhsa_system_sgpr_workgroup_id_y 0
		.amdhsa_system_sgpr_workgroup_id_z 0
		.amdhsa_system_sgpr_workgroup_info 0
		.amdhsa_system_vgpr_workitem_id 2
		.amdhsa_next_free_vgpr 253
		.amdhsa_next_free_sgpr 102
		.amdhsa_accum_offset 256
		.amdhsa_reserve_vcc 1
		.amdhsa_float_round_mode_32 0
		.amdhsa_float_round_mode_16_64 0
		.amdhsa_float_denorm_mode_32 3
		.amdhsa_float_denorm_mode_16_64 3
		.amdhsa_dx10_clamp 1
		.amdhsa_ieee_mode 1
		.amdhsa_fp16_overflow 0
		.amdhsa_tg_split 0
		.amdhsa_exception_fp_ieee_invalid_op 0
		.amdhsa_exception_fp_denorm_src 0
		.amdhsa_exception_fp_ieee_div_zero 0
		.amdhsa_exception_fp_ieee_overflow 0
		.amdhsa_exception_fp_ieee_underflow 0
		.amdhsa_exception_fp_ieee_inexact 0
		.amdhsa_exception_int_div_zero 0
	.end_amdhsa_kernel

amdhsa.kernels:
  - .agpr_count:     0
    .args:
      - .offset:         0
        .size:           280
        .value_kind:     by_value
      - .offset:         280
        .size:           4
        .value_kind:     hidden_block_count_x
      - .offset:         284
        .size:           4
        .value_kind:     hidden_block_count_y
      - .offset:         288
        .size:           4
        .value_kind:     hidden_block_count_z
      - .offset:         292
        .size:           2
        .value_kind:     hidden_group_size_x
      - .offset:         294
        .size:           2
        .value_kind:     hidden_group_size_y
      - .offset:         296
        .size:           2
        .value_kind:     hidden_group_size_z
      - .offset:         298
        .size:           2
        .value_kind:     hidden_remainder_x
      - .offset:         300
        .size:           2
        .value_kind:     hidden_remainder_y
      - .offset:         302
        .size:           2
        .value_kind:     hidden_remainder_z
      - .offset:         320
        .size:           8
        .value_kind:     hidden_global_offset_x
      - .offset:         328
        .size:           8
        .value_kind:     hidden_global_offset_y
      - .offset:         336
        .size:           8
        .value_kind:     hidden_global_offset_z
      - .offset:         344
        .size:           2
        .value_kind:     hidden_grid_dims
      - .offset:         368
        .size:           8
        .value_kind:     hidden_multigrid_sync_arg
      - .offset:         400
        .size:           4
        .value_kind:     hidden_dynamic_lds_size
    .group_segment_fixed_size: 16
    .kernarg_segment_align: 8
    .kernarg_segment_size: 536
    .language:       OpenCL C
    .language_version:
      - 2
      - 0
    .max_flat_workgroup_size: 512
    .name:           _Z8mega_fwd6Params
    .private_segment_fixed_size: 0
    .sgpr_count:     108
    .sgpr_spill_count: 6
    .symbol:         _Z8mega_fwd6Params.kd
    .uniform_work_group_size: 1
    .uses_dynamic_stack: false
    .vgpr_count:     253
    .vgpr_spill_count: 0
    .wavefront_size: 64
